# GDN chunk-prep phase: waves 4-7 delayed once by s_sleep 127 (~4 us) so the two waves per SIMD stop running the barrier-free program in lockstep (run 1)
# baseline (speedup 1.0000x reference)
; #define LAS __attribute__((address_space(3)))
; DI void gdn_prep_unit(int uid, const bf16* qkv, const bf16* psmall, const float* convw, const float* a_log, const float* dt_bias,
;                       unsigned char* G, float* glast, LAS unsigned char* wl, int lane) {
;     asm volatile("" : "+v"(lane));
;     asm volatile("" : "+s"(uid));
;     const int h = uid & 7, n = (uid >> 3) & 63, b = uid >> 9;
;     const int row0 = b * T + 64 * n;
;     const int r32 = lane & 31, hi = lane >> 5;
;     unsigned char* Gu = G + (size_t)uid * 40960;
;     bf16* Wn = (bf16*)Gu; bf16* QD = Wn + 4096; bf16* AT = QD + 4096; bf16* KDT = AT + 4096; bf16* UT = KDT + 4096;
;     LAS unsigned char* R0 = wl; LAS unsigned char* R1 = wl + 9216; LAS unsigned char* HX = wl + 18432;
; __global__ void __launch_bounds__(512, 2) mk_fwd(Args a) {
;     ...
;         for (int uid = gw; uid < 4096; uid += NGW)
;             gdn_prep_unit(uid, QKV, PS, (const float*)a.in[14], (const float*)a.in[15], (const float*)a.in[16], GB, GLAST, wl, lane);
.LBB0_618:
	v_readlane_b32 s2, v253, 59
	s_cmpk_gt_i32 s58, 0xfff
	v_readlane_b32 s3, v253, 60
	s_cbranch_scc1 .LBB0_638
	s_mov_b32 s77, 0
	v_writelane_b32 v252, s60, 0
	s_mov_b32 s78, s77
	v_mbcnt_lo_u32_b32 v0, -1, 0
	v_writelane_b32 v252, s61, 1
	v_writelane_b32 v252, s62, 2
	v_writelane_b32 v252, s63, 3
	v_writelane_b32 v252, s64, 4
	v_writelane_b32 v252, s65, 5
	v_writelane_b32 v252, s66, 6
	s_mov_b32 s79, s77
	v_writelane_b32 v252, s67, 7
	v_writelane_b32 v253, s74, 61
	v_mbcnt_hi_u32_b32 v135, -1, v0
	v_bfrev_b32_e32 v0, 0.5
	s_mov_b32 s76, s77
	v_mov_b64_e32 v[234:235], s[78:79]
	s_mov_b32 s0, s58
	v_writelane_b32 v252, s68, 8
	s_add_i32 s97, s95, 0x2400
	s_add_i32 s94, s95, 0x4800
	v_mov_b32_e32 v134, 0x3ecc95a3
	v_mov_b32_e32 v89, 0
	s_movk_i32 s81, 0x90
	v_lshl_or_b32 v136, v135, 2, v0
	v_mov_b64_e32 v[232:233], s[76:77]
	v_mov_b32_e32 v90, 0x3f317218
	v_mov_b32_e32 v137, 0x7f800000
	v_mov_b32_e32 v138, 0x7fc00000
	v_mov_b32_e32 v139, 0xff800000
	v_mov_b32_e32 v140, 0x90
	v_mov_b32_e32 v141, 0xfffffee0
	v_mov_b32_e32 v142, 0x120
	v_mov_b32_e32 v143, 0xffffff70
	v_mov_b32_e32 v144, 0x3e000000
	v_mov_b32_e32 v145, 0x1200
	v_writelane_b32 v253, s0, 62
	s_mov_b32 s80, s58
	v_writelane_b32 v252, s69, 9
	v_writelane_b32 v253, s1, 63
	v_writelane_b32 v252, s75, 10
	v_readfirstlane_b32 s98, v197
	s_nop 3
	s_cmpk_lt_u32 s98, 0x100
	s_cbranch_scc1 .Lp5stg_done
	s_sleep 127
.Lp5stg_done:
	s_branch .LBB0_621
